# nt hint also on the prep-phase U-row stores (plus the x-row loads of v134), otherwise identical to v108
# baseline (speedup 1.0000x reference)
.LBB0_19:
	s_or_b64 exec, exec, s[14:15]
	v_lshlrev_b64 v[28:29], 13, v[28:29]
	v_lshl_add_u64 v[32:33], v[30:31], 0, v[28:29]
	v_lshl_add_u64 v[48:49], v[32:33], 0, v[2:3]
	global_load_dwordx4 v[28:31], v[48:49], off nt
	global_load_dwordx4 v[40:43], v[48:49], off offset:1024 nt
	v_mov_b32_e32 v17, v3
	v_mov_b32_e32 v19, v3
	global_load_dwordx4 v[44:47], v[48:49], off offset:2048 nt
	v_lshl_add_u64 v[52:53], v[32:33], 0, v[16:17]
	v_lshl_add_u64 v[56:57], v[32:33], 0, v[18:19]
	global_load_dwordx4 v[48:51], v[48:49], off offset:3072 nt
	s_nop 0
	global_load_dwordx4 v[52:55], v[52:53], off nt
	s_nop 0
	global_load_dwordx4 v[56:59], v[56:57], off nt
	v_mov_b32_e32 v21, v3
	v_mov_b32_e32 v23, v3
	v_lshl_add_u64 v[60:61], v[32:33], 0, v[20:21]
	v_lshl_add_u64 v[32:33], v[32:33], 0, v[22:23]
	global_load_dwordx4 v[60:63], v[60:61], off nt
	s_nop 0
	global_load_dwordx4 v[64:67], v[32:33], off nt
	v_cmp_lt_i32_e32 vcc, v36, v37
	s_waitcnt vmcnt(7)
	v_pk_mul_f32 v[72:73], v[28:29], v[28:29]
	s_waitcnt vmcnt(6)
	v_pk_mul_f32 v[76:77], v[40:41], v[40:41]
	v_pk_mul_f32 v[32:33], v[30:31], v[30:31]
	v_pk_mul_f32 v[74:75], v[42:43], v[42:43]
	s_waitcnt vmcnt(5)
	v_pk_mul_f32 v[80:81], v[44:45], v[44:45]
	v_add_f32_e32 v19, v76, v77
	v_add_f32_e32 v21, v72, v73
	v_pk_mul_f32 v[78:79], v[46:47], v[46:47]
	s_waitcnt vmcnt(4)
	v_pk_mul_f32 v[84:85], v[48:49], v[48:49]
	s_waitcnt vmcnt(3)
	v_mov_b32_e32 v92, v53
	s_waitcnt vmcnt(2)
	v_mov_b32_e32 v93, v57
	v_add_f32_e32 v23, v80, v81
	v_add_f32_e32 v19, v19, v74
	v_add_f32_e32 v21, v21, v32
	v_pk_mul_f32 v[82:83], v[50:51], v[50:51]
	v_mov_b32_e32 v90, v52
	v_mov_b32_e32 v91, v56
	v_pk_mul_f32 v[92:93], v[92:93], v[92:93]
	v_add_f32_e32 v25, v84, v85
	v_add_f32_e32 v23, v23, v78
	v_add_f32_e32 v19, v19, v75
	v_add_f32_e32 v21, v21, v33
	v_mov_b32_e32 v86, v54
	v_mov_b32_e32 v87, v58
	s_waitcnt vmcnt(1)
	v_mov_b32_e32 v100, v61
	s_waitcnt vmcnt(0)
	v_mov_b32_e32 v101, v65
	v_pk_fma_f32 v[72:73], v[90:91], v[90:91], v[92:93]
	v_add_f32_e32 v25, v25, v82
	v_add_f32_e32 v23, v23, v79
	v_add_f32_e32 v19, v21, v19
	v_mov_b32_e32 v88, v55
	v_mov_b32_e32 v89, v59
	v_mov_b32_e32 v98, v60
	v_mov_b32_e32 v99, v64
	v_pk_mul_f32 v[100:101], v[100:101], v[100:101]
	v_pk_fma_f32 v[72:73], v[86:87], v[86:87], v[72:73]
	v_add_f32_e32 v25, v25, v83
	v_add_f32_e32 v19, v19, v23
	v_mov_b32_e32 v94, v62
	v_mov_b32_e32 v95, v66
	v_pk_fma_f32 v[76:77], v[98:99], v[98:99], v[100:101]
	v_pk_fma_f32 v[32:33], v[88:89], v[88:89], v[72:73]
	v_add_f32_e32 v19, v19, v25
	v_mov_b32_e32 v96, v63
	v_mov_b32_e32 v97, v67
	v_pk_fma_f32 v[76:77], v[94:95], v[94:95], v[76:77]
	v_add_f32_e32 v19, v19, v32
	v_pk_fma_f32 v[72:73], v[96:97], v[96:97], v[76:77]
	v_add_f32_e32 v19, v19, v33
	v_add_f32_e32 v19, v19, v72
	v_add_f32_e32 v19, v19, v73
	v_cndmask_b32_e32 v17, v35, v36, vcc
	v_lshlrev_b32_e32 v17, 2, v17
	v_add_f32_dpp v19, v19, v19 quad_perm:[1,0,3,2] row_mask:0xf bank_mask:0xf bound_ctrl:1
	v_cmp_lt_i32_e32 vcc, v38, v37
	v_mov_b32_e32 v25, v3
	v_add_f32_dpp v19, v19, v19 quad_perm:[2,3,0,1] row_mask:0xf bank_mask:0xf bound_ctrl:1
	v_cndmask_b32_e32 v21, v35, v38, vcc
	v_lshlrev_b32_e32 v21, 2, v21
	v_add_f32_dpp v19, v19, v19 row_half_mirror row_mask:0xf bank_mask:0xf bound_ctrl:1
	v_lshl_add_u64 v[32:33], v[26:27], 0, v[24:25]
	s_nop 0
	v_add_f32_dpp v19, v19, v19 row_mirror row_mask:0xf bank_mask:0xf bound_ctrl:1
	ds_bpermute_b32 v17, v17, v19
	s_waitcnt lgkmcnt(0)
	v_add_f32_e32 v17, v19, v17
	ds_bpermute_b32 v19, v21, v17
	s_waitcnt lgkmcnt(0)
	v_add_f32_e32 v17, v17, v19
	v_fmamk_f32 v17, v17, 0x3a000000, v34
	v_mul_f32_e32 v19, 0x4b800000, v17
	v_cmp_gt_f32_e32 vcc, s23, v17
	s_nop 1
	v_cndmask_b32_e32 v17, v17, v19, vcc
	v_rsq_f32_e32 v17, v17
	s_nop 0
	v_mul_f32_e32 v19, 0x45800000, v17
	v_cndmask_b32_e32 v72, v17, v19, vcc
	v_pk_mul_f32 v[26:27], v[28:29], v[72:73] op_sel_hi:[1,0]
	v_pk_mul_f32 v[28:29], v[30:31], v[72:73] op_sel_hi:[1,0]
	v_pk_mul_f32 v[26:27], v[182:183], v[26:27]
	v_pk_mul_f32 v[28:29], v[184:185], v[28:29]
	v_cvt_pk_bf16_f32 v26, v26, v27
	v_cvt_pk_bf16_f32 v27, v28, v29
	global_store_dwordx2 v[32:33], v[26:27], off nt
	v_pk_mul_f32 v[30:31], v[40:41], v[72:73] op_sel_hi:[1,0]
	v_pk_mul_f32 v[40:41], v[42:43], v[72:73] op_sel_hi:[1,0]
	v_pk_mul_f32 v[26:27], v[186:187], v[30:31]
	v_pk_mul_f32 v[28:29], v[188:189], v[40:41]
	v_cvt_pk_bf16_f32 v26, v26, v27
	v_cvt_pk_bf16_f32 v27, v28, v29
	global_store_dwordx2 v[32:33], v[26:27], off offset:512 nt
	v_pk_mul_f32 v[30:31], v[44:45], v[72:73] op_sel_hi:[1,0]
	v_pk_mul_f32 v[40:41], v[46:47], v[72:73] op_sel_hi:[1,0]
	v_pk_mul_f32 v[26:27], v[30:31], v[190:191]
	v_pk_mul_f32 v[28:29], v[40:41], v[192:193]
	v_cvt_pk_bf16_f32 v26, v26, v27
	v_cvt_pk_bf16_f32 v27, v28, v29
	global_store_dwordx2 v[32:33], v[26:27], off offset:1024 nt
	v_pk_mul_f32 v[30:31], v[48:49], v[72:73] op_sel_hi:[1,0]
	v_pk_mul_f32 v[40:41], v[50:51], v[72:73] op_sel_hi:[1,0]
	v_pk_mul_f32 v[26:27], v[30:31], v[194:195]
	v_pk_mul_f32 v[28:29], v[40:41], v[196:197]
	v_cvt_pk_bf16_f32 v26, v26, v27
	v_cvt_pk_bf16_f32 v27, v28, v29
	global_store_dwordx2 v[32:33], v[26:27], off offset:1536 nt
	v_pk_mul_f32 v[30:31], v[52:53], v[72:73] op_sel_hi:[1,0]
	v_pk_mul_f32 v[40:41], v[54:55], v[72:73] op_sel_hi:[1,0]
	v_pk_mul_f32 v[26:27], v[30:31], v[198:199]
	v_pk_mul_f32 v[28:29], v[40:41], v[200:201]
	v_cvt_pk_bf16_f32 v26, v26, v27
	v_cvt_pk_bf16_f32 v27, v28, v29
	global_store_dwordx2 v[32:33], v[26:27], off offset:2048 nt
	v_pk_mul_f32 v[30:31], v[56:57], v[72:73] op_sel_hi:[1,0]
	v_pk_mul_f32 v[40:41], v[58:59], v[72:73] op_sel_hi:[1,0]
	v_pk_mul_f32 v[26:27], v[30:31], v[202:203]
	v_pk_mul_f32 v[28:29], v[40:41], v[204:205]
	v_cvt_pk_bf16_f32 v26, v26, v27
	v_cvt_pk_bf16_f32 v27, v28, v29
	global_store_dwordx2 v[32:33], v[26:27], off offset:2560 nt
	v_pk_mul_f32 v[30:31], v[60:61], v[72:73] op_sel_hi:[1,0]
	v_pk_mul_f32 v[40:41], v[62:63], v[72:73] op_sel_hi:[1,0]
	v_pk_mul_f32 v[26:27], v[30:31], v[206:207]
	v_pk_mul_f32 v[28:29], v[40:41], v[208:209]
	v_cvt_pk_bf16_f32 v26, v26, v27
	v_cvt_pk_bf16_f32 v27, v28, v29
	global_store_dwordx2 v[32:33], v[26:27], off offset:3072 nt
	v_pk_mul_f32 v[30:31], v[64:65], v[72:73] op_sel_hi:[1,0]
	v_pk_mul_f32 v[40:41], v[66:67], v[72:73] op_sel_hi:[1,0]
	v_pk_mul_f32 v[26:27], v[30:31], v[210:211]
	v_pk_mul_f32 v[28:29], v[40:41], v[212:213]
	v_cvt_pk_bf16_f32 v26, v26, v27
	v_cvt_pk_bf16_f32 v27, v28, v29
	global_store_dwordx2 v[32:33], v[26:27], off offset:3584 nt
.LBB0_20:
	s_andn2_saveexec_b64 s[12:13], s[12:13]
	s_cbranch_execz .LBB0_9
	v_mov_b32_e32 v25, v3
	s_mov_b32 s11, s10
	v_lshl_add_u64 v[26:27], v[26:27], 0, v[24:25]
	v_mov_b64_e32 v[28:29], s[10:11]
	global_store_dwordx2 v[26:27], v[28:29], off nt
	global_store_dwordx2 v[26:27], v[28:29], off offset:512 nt
	global_store_dwordx2 v[26:27], v[28:29], off offset:1024 nt
	global_store_dwordx2 v[26:27], v[28:29], off offset:1536 nt
	global_store_dwordx2 v[26:27], v[28:29], off offset:2048 nt
	global_store_dwordx2 v[26:27], v[28:29], off offset:2560 nt
	global_store_dwordx2 v[26:27], v[28:29], off offset:3072 nt
	global_store_dwordx2 v[26:27], v[28:29], off offset:3584 nt
	s_branch .LBB0_9
